# cache policy: nt hint on the 8 write-once out stores of the final RMSNorm loop so L2 keeps the not-yet-read out rows; on top of v030
# speedup vs baseline: 1.0039x; 1.0039x over previous
; __device__ __forceinline__ void final_phase(float* x, const float* ssq, const float* gn, bool team) {
;     ...
;     for (int m = mbeg; m < mend; m += mstep) { float s = ssq[(size_t)m * 32 + (lane & 31)];
; #pragma unroll
;         for (int o = 1; o < 32; o <<= 1) s += __shfl_xor(s, o);
;         const float rs = __builtin_amdgcn_rsqf(s * (1.0f / D) + 1e-6f); f32x4* xr = (f32x4*)(x + (size_t)m * D) + lane; const f32x4* gr = (const f32x4*)gn + lane;
; #pragma unroll
;         for (int j = 0; j < 8; ++j) xr[64 * j] = xr[64 * j] * rs * gr[64 * j]; }
.LBB0_2364:
	global_load_dword v3, v[18:19], off
	global_load_dwordx4 v[76:79], v[14:15], off offset:-4096
	global_load_dwordx4 v[80:83], v[14:15], off offset:-3072
	global_load_dwordx4 v[84:87], v[14:15], off offset:-2048
	global_load_dwordx4 v[88:91], v[14:15], off offset:-1024
	global_load_dwordx4 v[92:95], v[14:15], off
	global_load_dwordx4 v[96:99], v[14:15], off offset:1024
	global_load_dwordx4 v[100:103], v[14:15], off offset:2048
	global_load_dwordx4 v[104:107], v[14:15], off offset:3072
	v_add_u32_e32 v0, v0, v2
	v_cmp_ge_i32_e32 vcc, v0, v22
	v_lshl_add_u64 v[18:19], v[18:19], 0, v[20:21]
	s_or_b64 s[0:1], vcc, s[0:1]
	s_waitcnt vmcnt(8)
	ds_bpermute_b32 v40, v23, v3
	s_waitcnt lgkmcnt(0)
	v_add_f32_e32 v3, v3, v40
	ds_bpermute_b32 v40, v24, v3
	s_waitcnt lgkmcnt(0)
	v_add_f32_e32 v3, v3, v40
	ds_bpermute_b32 v40, v25, v3
	s_waitcnt lgkmcnt(0)
	v_add_f32_e32 v3, v3, v40
	ds_bpermute_b32 v40, v26, v3
	s_waitcnt lgkmcnt(0)
	v_add_f32_e32 v3, v3, v40
	ds_bpermute_b32 v40, v27, v3
	s_waitcnt lgkmcnt(0)
	v_add_f32_e32 v3, v3, v40
	v_fmamk_f32 v3, v3, 0x3a000000, v1
	v_rsq_f32_e32 v40, v3
	s_waitcnt vmcnt(7)
	v_pk_mul_f32 v[76:77], v[76:77], v[40:41] op_sel_hi:[1,0]
	v_pk_mul_f32 v[78:79], v[78:79], v[40:41] op_sel_hi:[1,0]
	v_pk_mul_f32 v[76:77], v[44:45], v[76:77]
	v_pk_mul_f32 v[78:79], v[46:47], v[78:79]
	global_store_dwordx4 v[14:15], v[76:79], off offset:-4096 nt
	s_waitcnt vmcnt(7)
	v_pk_mul_f32 v[80:81], v[80:81], v[40:41] op_sel_hi:[1,0]
	v_pk_mul_f32 v[82:83], v[82:83], v[40:41] op_sel_hi:[1,0]
	v_pk_mul_f32 v[80:81], v[48:49], v[80:81]
	v_pk_mul_f32 v[82:83], v[50:51], v[82:83]
	global_store_dwordx4 v[14:15], v[80:83], off offset:-3072 nt
	s_waitcnt vmcnt(7)
	v_pk_mul_f32 v[84:85], v[84:85], v[40:41] op_sel_hi:[1,0]
	v_pk_mul_f32 v[86:87], v[86:87], v[40:41] op_sel_hi:[1,0]
	v_pk_mul_f32 v[84:85], v[52:53], v[84:85]
	v_pk_mul_f32 v[86:87], v[54:55], v[86:87]
	global_store_dwordx4 v[14:15], v[84:87], off offset:-2048 nt
	s_waitcnt vmcnt(7)
	v_pk_mul_f32 v[88:89], v[88:89], v[40:41] op_sel_hi:[1,0]
	v_pk_mul_f32 v[90:91], v[90:91], v[40:41] op_sel_hi:[1,0]
	v_pk_mul_f32 v[88:89], v[56:57], v[88:89]
	v_pk_mul_f32 v[90:91], v[58:59], v[90:91]
	global_store_dwordx4 v[14:15], v[88:91], off offset:-1024 nt
	s_waitcnt vmcnt(7)
	v_pk_mul_f32 v[92:93], v[92:93], v[40:41] op_sel_hi:[1,0]
	v_pk_mul_f32 v[94:95], v[94:95], v[40:41] op_sel_hi:[1,0]
	v_pk_mul_f32 v[92:93], v[60:61], v[92:93]
	v_pk_mul_f32 v[94:95], v[62:63], v[94:95]
	global_store_dwordx4 v[14:15], v[92:95], off nt
	s_waitcnt vmcnt(7)
	v_pk_mul_f32 v[96:97], v[96:97], v[40:41] op_sel_hi:[1,0]
	v_pk_mul_f32 v[98:99], v[98:99], v[40:41] op_sel_hi:[1,0]
	v_pk_mul_f32 v[96:97], v[64:65], v[96:97]
	v_pk_mul_f32 v[98:99], v[66:67], v[98:99]
	global_store_dwordx4 v[14:15], v[96:99], off offset:1024 nt
	s_waitcnt vmcnt(7)
	v_pk_mul_f32 v[100:101], v[100:101], v[40:41] op_sel_hi:[1,0]
	v_pk_mul_f32 v[102:103], v[102:103], v[40:41] op_sel_hi:[1,0]
	v_pk_mul_f32 v[100:101], v[68:69], v[100:101]
	v_pk_mul_f32 v[102:103], v[70:71], v[102:103]
	global_store_dwordx4 v[14:15], v[100:103], off offset:2048 nt
	s_waitcnt vmcnt(7)
	v_pk_mul_f32 v[104:105], v[104:105], v[40:41] op_sel_hi:[1,0]
	v_pk_mul_f32 v[106:107], v[106:107], v[40:41] op_sel_hi:[1,0]
	v_pk_mul_f32 v[104:105], v[72:73], v[104:105]
	v_pk_mul_f32 v[106:107], v[74:75], v[106:107]
	global_store_dwordx4 v[14:15], v[104:107], off offset:3072 nt
	v_lshl_add_u64 v[14:15], v[14:15], 0, v[16:17]
	s_andn2_b64 exec, exec, s[0:1]
	s_cbranch_execnz .LBB0_2364
